# v40 + redundant canonicalizing v_max removed in the diff-attention row-max reduction
# speedup vs baseline: 1.0074x; 1.0074x over previous
; DI float ex2(float x) { return __builtin_amdgcn_exp2f(x); }
; DI float red_max32(float x) { auto r = __builtin_amdgcn_permlane32_swap(__float_as_uint(x), __float_as_uint(x), false, false); return fmaxf(__uint_as_float(r[0]), __uint_as_float(r[1])); }
; DI void diff_attn_phase(unsigned char* lds, KParamPtr P, int wv, int l) {
;     ...
;             float mloc = NEGB;
;             const bool far = (q0w - (s0 + 31) >= 127);
;             if (far) {
; #pragma unroll
;               for (int i = 0; i < 16; ++i) mloc = fmaxf(mloc, s[i]);
;               mloc = fmaf(mloc, C1, bfar);
;             } else {
; #pragma unroll
;               for (int i = 0; i < 16; ++i) {
;                 int key = s0 + (i & 7) + 8 * hh + 16 * (i >> 3);
;                 int dist = t - key; int dd = dist < 0 ? 0 : (dist > 127 ? 127 : dist);
;                 const float tb = tab[col * 128 + dd];
;                 float z = fmaf(s[i], C1, tb); z = dist < 0 ? NEGB : z;
;                 s[i] = z; mloc = fmaxf(mloc, z);
;               }
;             }
;             mloc = red_max32(mloc);
;             const float m_new = (mloc > m_run + 16.f) ? mloc : m_run;
;             const float alpha = ex2(m_run - m_new);
;             float ls = 0.f;
;             if (far) {
;               const float boff_ = bfar - m_new;
; #pragma unroll
;               for (int i = 0; i < 16; ++i) { float p = ex2(fmaf(s[i], C1, boff_)); s[i] = p; ls += p; }
;             } else {
; #pragma unroll
;               for (int i = 0; i < 16; ++i) { float p = ex2(s[i] - m_new); s[i] = p; ls += p; }
;             }
;             l_run = l_run * alpha + ls; m_run = m_new;
.LBB0_222:
	s_andn2_saveexec_b64 s[4:5], s[22:23]
	s_nop 7
	v_max3_f32 v0, v80, s52, v81
	v_max3_f32 v0, v0, v82, v83
	v_max3_f32 v0, v0, v84, v85
	v_max3_f32 v0, v0, v86, v87
	v_max3_f32 v0, v0, v88, v89
	v_max3_f32 v0, v0, v90, v91
	v_max3_f32 v0, v0, v92, v93
	v_max3_f32 v0, v0, v94, v95
	v_fmamk_f32 v0, v0, 0x3e38aa3b, v223
	s_or_b64 exec, exec, s[4:5]
	v_mov_b32_e32 v15, v0
	s_nop 1
	v_permlane32_swap_b32_e32 v0, v15
	v_max_f32_e32 v0, v0, v15
	v_add_f32_e32 v15, 0x41800000, v225
	v_cmp_gt_f32_e64 s[4:5], v0, v15
	s_nop 1
	v_cndmask_b32_e64 v15, v225, v0, s[4:5]
	s_and_saveexec_b64 s[4:5], vcc
	s_xor_b64 s[4:5], exec, s[4:5]
	s_cbranch_execz .LBB0_226
	v_sub_f32_e32 v0, v80, v15
	v_exp_f32_e32 v96, v0
	v_sub_f32_e32 v0, v81, v15
	v_exp_f32_e32 v97, v0
	v_sub_f32_e32 v0, v82, v15
	v_exp_f32_e32 v98, v0
	v_sub_f32_e32 v80, v83, v15
	v_exp_f32_e32 v99, v80
	v_sub_f32_e32 v80, v84, v15
	v_add_f32_e32 v0, 0, v96
	v_exp_f32_e32 v100, v80
	v_sub_f32_e32 v80, v85, v15
	v_add_f32_e32 v0, v97, v0
	v_exp_f32_e32 v101, v80
	v_sub_f32_e32 v80, v86, v15
	v_add_f32_e32 v0, v98, v0
	v_exp_f32_e32 v102, v80
	v_sub_f32_e32 v80, v87, v15
	v_add_f32_e32 v0, v99, v0
	v_exp_f32_e32 v103, v80
	v_sub_f32_e32 v80, v88, v15
	v_add_f32_e32 v0, v100, v0
	v_exp_f32_e32 v104, v80
	v_sub_f32_e32 v80, v89, v15
	v_add_f32_e32 v0, v101, v0
	v_exp_f32_e32 v105, v80
	v_sub_f32_e32 v80, v90, v15
	v_add_f32_e32 v0, v102, v0
	v_exp_f32_e32 v106, v80
	v_sub_f32_e32 v80, v91, v15
	v_add_f32_e32 v0, v103, v0
	v_exp_f32_e32 v107, v80
	v_sub_f32_e32 v80, v92, v15
	v_add_f32_e32 v0, v104, v0
	v_exp_f32_e32 v108, v80
	v_sub_f32_e32 v80, v93, v15
	v_add_f32_e32 v0, v105, v0
	v_exp_f32_e32 v109, v80
	v_sub_f32_e32 v80, v94, v15
	v_add_f32_e32 v0, v106, v0
	v_exp_f32_e32 v110, v80
	v_add_f32_e32 v0, v107, v0
	v_add_f32_e32 v0, v108, v0
	v_add_f32_e32 v0, v109, v0
	v_add_f32_e32 v219, v110, v0
	v_sub_f32_e32 v111, v95, v15

; DI float ex2(float x) { return __builtin_amdgcn_exp2f(x); }
; DI float red_max32(float x) { auto r = __builtin_amdgcn_permlane32_swap(__float_as_uint(x), __float_as_uint(x), false, false); return fmaxf(__uint_as_float(r[0]), __uint_as_float(r[1])); }
; DI void diff_attn_phase(unsigned char* lds, KParamPtr P, int wv, int l) {
;     ...
;             float mloc = NEGB;
;             const bool far = (q0w - (s0 + 31) >= 127);
;             if (far) {
; #pragma unroll
;               for (int i = 0; i < 16; ++i) mloc = fmaxf(mloc, s[i]);
;               mloc = fmaf(mloc, C1, bfar);
;             } else {
; #pragma unroll
;               for (int i = 0; i < 16; ++i) {
;                 int key = s0 + (i & 7) + 8 * hh + 16 * (i >> 3);
;                 int dist = t - key; int dd = dist < 0 ? 0 : (dist > 127 ? 127 : dist);
;                 const float tb = tab[col * 128 + dd];
;                 float z = fmaf(s[i], C1, tb); z = dist < 0 ? NEGB : z;
;                 s[i] = z; mloc = fmaxf(mloc, z);
;               }
;             }
;             mloc = red_max32(mloc);
;             const float m_new = (mloc > m_run + 16.f) ? mloc : m_run;
;             const float alpha = ex2(m_run - m_new);
;             float ls = 0.f;
;             if (far) {
;               const float boff_ = bfar - m_new;
; #pragma unroll
;               for (int i = 0; i < 16; ++i) { float p = ex2(fmaf(s[i], C1, boff_)); s[i] = p; ls += p; }
;             } else {
; #pragma unroll
;               for (int i = 0; i < 16; ++i) { float p = ex2(s[i] - m_new); s[i] = p; ls += p; }
;             }
;             l_run = l_run * alpha + ls; m_run = m_new;
.LBB0_234:
	s_andn2_saveexec_b64 s[4:5], s[22:23]
	s_nop 7
	v_max3_f32 v0, v80, s52, v81
	v_max3_f32 v0, v0, v82, v83
	v_max3_f32 v0, v0, v84, v85
	v_max3_f32 v0, v0, v86, v87
	v_max3_f32 v0, v0, v88, v89
	v_max3_f32 v0, v0, v90, v91
	v_max3_f32 v0, v0, v92, v93
	v_max3_f32 v0, v0, v94, v95
	v_fmamk_f32 v0, v0, 0x3e38aa3b, v223
	s_or_b64 exec, exec, s[4:5]
	v_mov_b32_e32 v14, v0
	s_nop 1
	v_permlane32_swap_b32_e32 v0, v14
	v_max_f32_e32 v0, v0, v14
	v_add_f32_e32 v14, 0x41800000, v225
	v_cmp_gt_f32_e64 s[4:5], v0, v14
	s_nop 1
	v_cndmask_b32_e64 v14, v225, v0, s[4:5]
	s_and_saveexec_b64 s[4:5], vcc
	s_xor_b64 s[4:5], exec, s[4:5]
	s_cbranch_execz .LBB0_238
	v_sub_f32_e32 v0, v80, v14
	v_exp_f32_e32 v96, v0
	v_sub_f32_e32 v0, v81, v14
	v_exp_f32_e32 v97, v0
	v_sub_f32_e32 v0, v82, v14
	v_exp_f32_e32 v98, v0
	v_sub_f32_e32 v15, v83, v14
	v_exp_f32_e32 v99, v15
	v_sub_f32_e32 v15, v84, v14
	v_add_f32_e32 v0, 0, v96
	v_exp_f32_e32 v100, v15
	v_sub_f32_e32 v15, v85, v14
	v_add_f32_e32 v0, v97, v0
	v_exp_f32_e32 v101, v15
	v_sub_f32_e32 v15, v86, v14
	v_add_f32_e32 v0, v98, v0
	v_exp_f32_e32 v102, v15
	v_sub_f32_e32 v15, v87, v14
	v_add_f32_e32 v0, v99, v0
	v_exp_f32_e32 v103, v15
	v_sub_f32_e32 v15, v88, v14
	v_add_f32_e32 v0, v100, v0
	v_exp_f32_e32 v104, v15
	v_sub_f32_e32 v15, v89, v14
	v_add_f32_e32 v0, v101, v0
	v_exp_f32_e32 v105, v15
	v_sub_f32_e32 v15, v90, v14
	v_add_f32_e32 v0, v102, v0
	v_exp_f32_e32 v106, v15
	v_sub_f32_e32 v15, v91, v14
	v_add_f32_e32 v0, v103, v0
	v_exp_f32_e32 v107, v15
	v_sub_f32_e32 v15, v92, v14
	v_add_f32_e32 v0, v104, v0
	v_exp_f32_e32 v108, v15
	v_sub_f32_e32 v15, v93, v14
	v_add_f32_e32 v0, v105, v0
	v_exp_f32_e32 v109, v15
	v_sub_f32_e32 v15, v94, v14
	v_add_f32_e32 v0, v106, v0
	v_exp_f32_e32 v110, v15
	v_add_f32_e32 v0, v107, v0
	v_add_f32_e32 v0, v108, v0
	v_add_f32_e32 v0, v109, v0
	v_add_f32_e32 v219, v110, v0
	v_sub_f32_e32 v15, v95, v14
